# v56 plus nt hints on the adaLN weight loads, the layer-0 weight-conversion loads and the row-phase MIX loads (all read once)
# speedup vs baseline: 1.0280x; 1.0004x over previous
.LBB0_478:
	v_lshlrev_b64 v[82:83], 12, v[82:83]
	v_ashrrev_i32_e32 v86, 10, v130
	v_lshl_add_u64 v[82:83], v[84:85], 0, v[82:83]
	v_lshlrev_b32_e32 v130, 2, v98
	v_add_u32_e32 v86, 1, v86
	v_lshl_add_u64 v[82:83], v[82:83], 0, v[130:131]
	v_cndmask_b32_e64 v132, v86, 0, s[0:1]
	global_load_dwordx4 v[94:97], v[82:83], off nt
	global_load_dwordx4 v[90:93], v[82:83], off offset:1024 nt
	global_load_dwordx4 v[86:89], v[82:83], off offset:2048 nt
	s_nop 0
	global_load_dwordx4 v[82:85], v[82:83], off offset:3072 nt
	v_cndmask_b32_e64 v133, 0, 1, s[4:5]
	v_cmp_ne_u32_e64 s[0:1], 1, v133
	s_andn2_b64 vcc, exec, s[4:5]
	s_cbranch_vccnz .LBB0_480
	v_lshlrev_b64 v[10:11], 11, v[128:129]
	v_lshl_add_u64 v[42:43], v[100:101], 0, v[10:11]
	global_load_dwordx2 v[112:113], v[42:43], off nt
	v_add_u32_e32 v44, s20, v132
	global_load_dwordx2 v[116:117], v[42:43], off offset:512 nt
	global_load_dwordx4 v[10:13], v[108:109], off
	global_load_dwordx4 v[26:29], v[108:109], off offset:1024
	global_load_dwordx2 v[120:121], v[42:43], off offset:1024 nt
	global_load_dwordx4 v[38:41], v[108:109], off offset:2048
	global_load_dwordx4 v[74:77], v[108:109], off offset:3072
	v_mad_i64_i32 v[78:79], s[6:7], v44, s3, v[110:111]
	global_load_dwordx2 v[124:125], v[42:43], off offset:1536 nt
	s_nop 0
	global_load_dwordx4 v[42:45], v[78:79], off
	global_load_dwordx4 v[54:57], v[78:79], off offset:1024
	global_load_dwordx4 v[66:69], v[78:79], off offset:2048
	s_nop 0
	global_load_dwordx4 v[78:81], v[78:79], off offset:3072
	s_waitcnt vmcnt(10)
	v_lshlrev_b32_e32 v118, 16, v116
	v_and_b32_e32 v119, 0xffff0000, v116
	v_lshlrev_b32_e32 v116, 16, v117
	v_lshlrev_b32_e32 v114, 16, v112
	v_and_b32_e32 v115, 0xffff0000, v112
	v_lshlrev_b32_e32 v112, 16, v113
	v_and_b32_e32 v113, 0xffff0000, v113
	v_and_b32_e32 v117, 0xffff0000, v117
	s_waitcnt vmcnt(7)
	v_lshlrev_b32_e32 v122, 16, v120
	v_and_b32_e32 v123, 0xffff0000, v120
	v_lshlrev_b32_e32 v120, 16, v121
	v_and_b32_e32 v121, 0xffff0000, v121
	s_waitcnt vmcnt(4)
	v_lshlrev_b32_e32 v126, 16, v124
	v_and_b32_e32 v127, 0xffff0000, v124
	v_lshlrev_b32_e32 v124, 16, v125
	v_and_b32_e32 v125, 0xffff0000, v125

.LBB0_511:
	v_lshl_add_u64 v[18:19], v[60:61], 0, s[6:7]
	v_add_co_u32_e64 v36, s[0:1], s3, v18
	ds_read_b128 v[10:13], v63
	ds_read_b128 v[14:17], v63 offset:16
	ds_read_b128 v[2:5], v63 offset:32
	ds_read_b128 v[38:41], v63 offset:4096
	ds_read_b128 v[28:31], v63 offset:8192
	ds_read_b128 v[20:23], v63 offset:8208
	ds_read_b128 v[32:35], v63 offset:12288
	ds_read_b128 v[42:45], v63 offset:12304
	ds_read_b128 v[46:49], v63 offset:16384
	ds_read_b128 v[24:27], v63 offset:16400
	v_addc_co_u32_e64 v37, s[0:1], 0, v19, s[0:1]
	s_mov_b32 s0, 0xc000
	s_nop 0
	v_add_co_u32_e64 v64, s[0:1], s0, v18
	global_load_dword v62, v[18:19], off nt
	s_nop 0
	v_addc_co_u32_e64 v65, s[0:1], 0, v19, s[0:1]
	s_mov_b32 s0, 0x12000
	s_nop 0
	v_add_co_u32_e64 v66, s[0:1], s0, v18
	s_waitcnt lgkmcnt(0)
	v_mov_b32_e32 v80, v10
	v_addc_co_u32_e64 v67, s[0:1], 0, v19, s[0:1]
	s_mov_b32 s0, 0x18000
	s_nop 0
	v_add_co_u32_e64 v68, s[0:1], s0, v18
	v_mov_b32_e32 v81, v46
	s_nop 0
	v_addc_co_u32_e64 v69, s[0:1], 0, v19, s[0:1]
	s_mov_b32 s0, 0x1e000
	s_nop 0
	v_add_co_u32_e64 v70, s[0:1], s0, v18
	v_mov_b32_e32 v46, v11
	s_nop 0
	v_addc_co_u32_e64 v71, s[0:1], 0, v19, s[0:1]
	s_mov_b32 s0, 0x24000
	s_nop 0
	v_add_co_u32_e64 v72, s[0:1], s0, v18
	v_mov_b32_e32 v78, v32
	s_nop 0
	v_addc_co_u32_e64 v73, s[0:1], 0, v19, s[0:1]
	s_mov_b32 s0, 0x2a000
	s_nop 0
	v_add_co_u32_e64 v10, s[0:1], s0, v18
	v_mov_b32_e32 v79, v28
	s_nop 0
	v_addc_co_u32_e64 v11, s[0:1], 0, v19, s[0:1]
	global_load_dword v84, v[36:37], off nt
	s_nop 0
	global_load_dword v64, v[64:65], off nt
	s_nop 0
	global_load_dword v66, v[66:67], off nt
	s_nop 0
	global_load_dword v86, v[68:69], off nt
	global_load_dword v88, v[70:71], off nt
	global_load_dword v76, v[72:73], off nt
	global_load_dword v74, v[10:11], off nt
	s_mov_b32 s0, 0x30000
	v_mov_b32_e32 v28, v33
	v_mov_b32_e32 v32, v34
	v_mov_b32_e32 v33, v30
	v_mov_b32_e32 v82, v12
	v_mov_b32_e32 v83, v48
	v_mov_b32_e32 v30, v35
	v_mov_b32_e32 v48, v13
	ds_read_b128 v[34:37], v63 offset:4112
	ds_read_b128 v[10:13], v63 offset:48
	s_add_u32 s6, s6, 0x60000
	s_addc_u32 s7, s7, 0
	s_cmp_eq_u32 s6, 0x600000
	s_waitcnt vmcnt(7)
	v_fmac_f32_e32 v55, v62, v38
	v_add_co_u32_e64 v38, s[0:1], s0, v18
	v_pk_fma_f32 v[8:9], v[62:63], v[78:79], v[8:9] op_sel_hi:[0,1,1]
	v_pk_fma_f32 v[6:7], v[62:63], v[80:81], v[6:7] op_sel_hi:[0,1,1]
	s_waitcnt vmcnt(6)
	v_fmac_f32_e32 v55, v84, v39
	v_addc_co_u32_e64 v39, s[0:1], 0, v19, s[0:1]
	s_mov_b32 s0, 0x36000
	v_pk_fma_f32 v[8:9], v[84:85], v[28:29], v[8:9] op_sel_hi:[0,1,1]
	v_pk_fma_f32 v[28:29], v[84:85], v[46:47], v[6:7] op_sel_hi:[0,1,1]
	v_add_co_u32_e64 v46, s[0:1], s0, v18
	s_waitcnt vmcnt(5)
	v_fmac_f32_e32 v55, v64, v40
	v_addc_co_u32_e64 v47, s[0:1], 0, v19, s[0:1]
	s_mov_b32 s0, 0x3c000
	s_nop 0
	v_add_co_u32_e64 v40, s[0:1], s0, v18
	s_waitcnt vmcnt(4)
	v_fmac_f32_e32 v55, v66, v41
	v_addc_co_u32_e64 v41, s[0:1], 0, v19, s[0:1]
	s_mov_b32 s0, 0x42000
	v_pk_fma_f32 v[32:33], v[64:65], v[32:33], v[8:9] op_sel_hi:[0,1,1]
	v_pk_fma_f32 v[28:29], v[64:65], v[82:83], v[28:29] op_sel_hi:[0,1,1]
	v_add_co_u32_e64 v64, s[0:1], s0, v18
	v_pk_fma_f32 v[30:31], v[66:67], v[30:31], v[32:33] op_sel_hi:[0,1,1]
	s_nop 0
	v_addc_co_u32_e64 v65, s[0:1], 0, v19, s[0:1]
	s_mov_b32 s0, 0x48000
	s_nop 0
	v_add_co_u32_e64 v32, s[0:1], s0, v18
	v_pk_fma_f32 v[28:29], v[66:67], v[48:49], v[28:29] op_sel_hi:[0,1,1]
	s_nop 0
	v_addc_co_u32_e64 v33, s[0:1], 0, v19, s[0:1]
	s_mov_b32 s0, 0x4e000
	s_nop 0
	v_add_co_u32_e64 v78, s[0:1], s0, v18
	ds_read_b128 v[6:9], v63 offset:4128
	s_nop 0
	v_addc_co_u32_e64 v79, s[0:1], 0, v19, s[0:1]
	s_mov_b32 s0, 0x54000
	s_nop 0
	v_add_co_u32_e64 v48, s[0:1], s0, v18
	s_waitcnt vmcnt(3) lgkmcnt(2)
	v_fmac_f32_e32 v55, v86, v34
	v_addc_co_u32_e64 v49, s[0:1], 0, v19, s[0:1]
	s_mov_b32 s0, 0x5a000
	s_nop 0
	v_add_co_u32_e64 v18, s[0:1], s0, v18
	s_waitcnt vmcnt(2)
	v_fmac_f32_e32 v55, v88, v35
	v_addc_co_u32_e64 v19, s[0:1], 0, v19, s[0:1]
	global_load_dword v72, v[38:39], off nt
	global_load_dword v70, v[46:47], off nt
	global_load_dword v68, v[40:41], off nt
	global_load_dword v66, v[64:65], off nt
	s_nop 0
	global_load_dword v64, v[32:33], off nt
	global_load_dword v62, v[78:79], off nt
	s_nop 0
	global_load_dword v48, v[48:49], off nt
	s_nop 0
	global_load_dword v46, v[18:19], off nt
	v_mov_b32_e32 v18, v42
	v_mov_b32_e32 v19, v20
	v_mov_b32_e32 v38, v14
	v_mov_b32_e32 v39, v24
	v_mov_b32_e32 v20, v43
	v_mov_b32_e32 v24, v15
	v_pk_fma_f32 v[18:19], v[86:87], v[18:19], v[30:31] op_sel_hi:[0,1,1]
	v_pk_fma_f32 v[38:39], v[86:87], v[38:39], v[28:29] op_sel_hi:[0,1,1]
	v_mov_b32_e32 v32, v44
	v_mov_b32_e32 v33, v22
	v_mov_b32_e32 v42, v16
	v_mov_b32_e32 v43, v26
	v_pk_fma_f32 v[34:35], v[88:89], v[20:21], v[18:19] op_sel_hi:[0,1,1]
	v_pk_fma_f32 v[24:25], v[88:89], v[24:25], v[38:39] op_sel_hi:[0,1,1]
	v_mov_b32_e32 v22, v45
	v_mov_b32_e32 v26, v17
	ds_read_b128 v[14:17], v63 offset:8224
	ds_read_b128 v[28:31], v63 offset:12320
	ds_read_b128 v[18:21], v63 offset:16416
	s_waitcnt vmcnt(9)
	v_pk_fma_f32 v[40:41], v[76:77], v[32:33], v[34:35] op_sel_hi:[0,1,1]
	v_pk_fma_f32 v[24:25], v[76:77], v[42:43], v[24:25] op_sel_hi:[0,1,1]
	v_fmac_f32_e32 v55, v76, v36
	s_waitcnt vmcnt(8)
	v_fmac_f32_e32 v55, v74, v37
	ds_read_b128 v[36:39], v63 offset:8240
	v_pk_fma_f32 v[44:45], v[74:75], v[22:23], v[40:41] op_sel_hi:[0,1,1]
	ds_read_b128 v[40:43], v63 offset:12336
	v_pk_fma_f32 v[26:27], v[74:75], v[26:27], v[24:25] op_sel_hi:[0,1,1]
	ds_read_b128 v[22:25], v63 offset:16432
	ds_read_b128 v[32:35], v63 offset:4144
	s_waitcnt lgkmcnt(5)
	v_mov_b32_e32 v74, v28
	v_mov_b32_e32 v75, v14
	v_mov_b32_e32 v14, v29
	v_mov_b32_e32 v28, v30
	v_mov_b32_e32 v29, v16
	v_mov_b32_e32 v16, v31
	v_mov_b32_e32 v30, v2
	s_waitcnt lgkmcnt(4)
	v_mov_b32_e32 v31, v18
	v_mov_b32_e32 v18, v3
	v_mov_b32_e32 v2, v4
	v_mov_b32_e32 v3, v20
	v_mov_b32_e32 v20, v5
	s_waitcnt lgkmcnt(2)
	v_mov_b32_e32 v4, v40
	v_mov_b32_e32 v5, v36
	v_mov_b32_e32 v36, v41
	v_mov_b32_e32 v40, v42
	v_mov_b32_e32 v41, v38
	v_mov_b32_e32 v38, v43
	v_mov_b32_e32 v42, v10
	s_waitcnt lgkmcnt(1)
	v_mov_b32_e32 v43, v22
	v_mov_b32_e32 v22, v11
	v_mov_b32_e32 v10, v12
	v_mov_b32_e32 v11, v24
	v_mov_b32_e32 v24, v13
	v_add_u32_e32 v63, 64, v63
	s_waitcnt vmcnt(7)
	v_fmac_f32_e32 v55, v72, v6
	v_pk_fma_f32 v[12:13], v[72:73], v[74:75], v[44:45] op_sel_hi:[0,1,1]
	v_pk_fma_f32 v[26:27], v[72:73], v[30:31], v[26:27] op_sel_hi:[0,1,1]
	s_waitcnt vmcnt(6)
	v_fmac_f32_e32 v55, v70, v7
	v_pk_fma_f32 v[6:7], v[70:71], v[14:15], v[12:13] op_sel_hi:[0,1,1]
	v_pk_fma_f32 v[12:13], v[70:71], v[18:19], v[26:27] op_sel_hi:[0,1,1]
	s_waitcnt vmcnt(5)
	v_fmac_f32_e32 v55, v68, v8
	v_pk_fma_f32 v[6:7], v[68:69], v[28:29], v[6:7] op_sel_hi:[0,1,1]
	v_pk_fma_f32 v[2:3], v[68:69], v[2:3], v[12:13] op_sel_hi:[0,1,1]
	s_waitcnt vmcnt(4)
	v_fmac_f32_e32 v55, v66, v9
	v_pk_fma_f32 v[6:7], v[66:67], v[16:17], v[6:7] op_sel_hi:[0,1,1]
	v_pk_fma_f32 v[2:3], v[66:67], v[20:21], v[2:3] op_sel_hi:[0,1,1]
	s_waitcnt vmcnt(3) lgkmcnt(0)
	v_fmac_f32_e32 v55, v64, v32
	v_pk_fma_f32 v[4:5], v[64:65], v[4:5], v[6:7] op_sel_hi:[0,1,1]
	v_pk_fma_f32 v[2:3], v[64:65], v[42:43], v[2:3] op_sel_hi:[0,1,1]
	s_waitcnt vmcnt(2)
	v_fmac_f32_e32 v55, v62, v33
	v_pk_fma_f32 v[4:5], v[62:63], v[36:37], v[4:5] op_sel_hi:[0,1,1]
	v_pk_fma_f32 v[2:3], v[62:63], v[22:23], v[2:3] op_sel_hi:[0,1,1]
	s_waitcnt vmcnt(1)
	v_fmac_f32_e32 v55, v48, v34
	v_pk_fma_f32 v[4:5], v[48:49], v[40:41], v[4:5] op_sel_hi:[0,1,1]
	v_pk_fma_f32 v[2:3], v[48:49], v[10:11], v[2:3] op_sel_hi:[0,1,1]
	s_waitcnt vmcnt(0)
	v_fmac_f32_e32 v55, v46, v35
	v_pk_fma_f32 v[8:9], v[46:47], v[38:39], v[4:5] op_sel_hi:[0,1,1]
	v_pk_fma_f32 v[6:7], v[46:47], v[24:25], v[2:3] op_sel_hi:[0,1,1]
	s_cbranch_scc0 .LBB0_511
	ds_write_b32 v54, v6 offset:20480
	ds_write2st64_b32 v53, v55, v9 offset0:81 offset1:82
	ds_write2st64_b32 v53, v8, v7 offset0:83 offset1:84
	s_waitcnt lgkmcnt(0)
	s_barrier
	s_and_saveexec_b64 s[0:1], vcc
	s_cbranch_execz .LBB0_509
	s_mul_i32 s6, s13, 0x1800
	s_add_i32 s6, s6, s4
	v_or_b32_e32 v2, s6, v50
	v_readlane_b32 s36, v254, 27
	v_ashrrev_i32_e32 v3, 31, v2
	v_readlane_b32 s38, v254, 29
	v_readlane_b32 s39, v254, 30
	s_mul_i32 s6, s13, 5
	s_add_i32 s7, s6, 2
	v_lshl_add_u64 v[2:3], v[2:3], 2, s[38:39]
	global_load_dword v32, v[2:3], off
	ds_read2st64_b32 v[4:5], v52 offset0:80 offset1:81
	ds_read2st64_b32 v[6:7], v52 offset0:84 offset1:85
	ds_read2st64_b32 v[8:9], v52 offset0:86 offset1:87
	ds_read2st64_b32 v[10:11], v52 offset0:82 offset1:83
	ds_read2st64_b32 v[12:13], v52 offset0:90 offset1:91
	ds_read2st64_b32 v[14:15], v52 offset0:94 offset1:95
	ds_read2st64_b32 v[16:17], v52 offset0:92 offset1:93
	ds_read2st64_b32 v[18:19], v52 offset0:88 offset1:89
	ds_read2st64_b32 v[20:21], v52 offset0:96 offset1:97
	ds_read2st64_b32 v[22:23], v52 offset0:98 offset1:99
	s_waitcnt lgkmcnt(8)
	v_add_f32_e32 v4, v4, v7
	v_lshl_add_u64 v[2:3], s[4:5], 2, v[56:57]
	s_waitcnt lgkmcnt(7)
	v_add_f32_e32 v5, v5, v8
	s_waitcnt lgkmcnt(6)
	v_add_f32_e32 v7, v10, v9
	s_waitcnt lgkmcnt(2)
	v_add_f32_e32 v8, v11, v18
	v_add_f32_e32 v6, v6, v19
	v_add_f32_e32 v4, v4, v12
	v_mad_i64_i32 v[24:25], s[4:5], s6, v204, v[2:3]
	v_add_f32_e32 v5, v5, v13
	v_add_f32_e32 v7, v7, v16
	v_add_f32_e32 v8, v8, v17
	v_add_f32_e32 v6, v6, v14
	v_add_f32_e32 v4, v4, v15
	s_add_i32 s4, s6, 1
	s_add_i32 s13, s6, 3
	s_add_i32 s6, s6, 4
	s_waitcnt lgkmcnt(1)
	v_add_f32_e32 v5, v5, v20
	v_add_f32_e32 v7, v7, v21
	s_waitcnt lgkmcnt(0)
	v_add_f32_e32 v8, v8, v22
	v_add_f32_e32 v6, v6, v23
	v_readlane_b32 s37, v254, 28
	v_readlane_b32 s40, v254, 31
	v_readlane_b32 s41, v254, 32
	v_readlane_b32 s42, v254, 33
	v_readlane_b32 s43, v254, 34
	v_readlane_b32 s44, v254, 35
	v_readlane_b32 s45, v254, 36
	v_readlane_b32 s46, v254, 37
	v_readlane_b32 s47, v254, 38
	v_readlane_b32 s48, v254, 39
	v_readlane_b32 s49, v254, 40
	v_readlane_b32 s50, v254, 41
	v_readlane_b32 s51, v254, 42
	v_mad_i64_i32 v[26:27], s[4:5], s4, v204, v[2:3]
	v_mad_i64_i32 v[28:29], s[4:5], s7, v204, v[2:3]
	v_mad_i64_i32 v[30:31], s[4:5], s13, v204, v[2:3]
	v_mad_i64_i32 v[2:3], s[4:5], s6, v204, v[2:3]
	s_waitcnt vmcnt(0)
	v_add_f32_e32 v4, v32, v4
	v_add_f32_e32 v5, v32, v5
	v_add_f32_e32 v7, v32, v7
	v_add_f32_e32 v8, v32, v8
	v_add_f32_e32 v6, v32, v6
	global_store_dword v[24:25], v4, off
	global_store_dword v[26:27], v5, off
	global_store_dword v[28:29], v7, off
	global_store_dword v[30:31], v8, off
	global_store_dword v[2:3], v6, off
	s_branch .LBB0_509

.LBB0_531:
	s_lshl_b32 s10, s24, 6
	v_or_b32_e32 v2, s10, v4
	s_add_i32 s24, s20, -1
	s_lshl_b32 s11, s22, 6
	v_min_i32_e32 v2, s24, v2
	v_ashrrev_i32_e32 v3, 31, v2
	v_add_u32_e32 v53, s11, v5
	v_lshl_add_u64 v[2:3], v[2:3], 2, s[6:7]
	v_mad_u64_u32 v[54:55], s[6:7], v53, s20, 0
	v_ashrrev_i32_e32 v57, 31, v53
	v_mov_b32_e32 v56, v55
	v_mad_u64_u32 v[56:57], s[6:7], v57, s20, v[56:57]
	v_add_u32_e32 v53, s11, v6
	v_mov_b32_e32 v55, v56
	v_mad_u64_u32 v[56:57], s[6:7], v53, s20, 0
	v_ashrrev_i32_e32 v59, 31, v53
	v_mov_b32_e32 v58, v57
	v_mad_u64_u32 v[58:59], s[6:7], v59, s20, v[58:59]
	v_add_u32_e32 v53, s11, v7
	v_mov_b32_e32 v57, v58
	v_mad_u64_u32 v[58:59], s[6:7], v53, s20, 0
	v_ashrrev_i32_e32 v61, 31, v53
	v_mov_b32_e32 v60, v59
	v_mad_u64_u32 v[60:61], s[6:7], v61, s20, v[60:61]
	v_add_u32_e32 v53, s11, v8
	v_mov_b32_e32 v59, v60
	v_mad_u64_u32 v[60:61], s[6:7], v53, s20, 0
	v_ashrrev_i32_e32 v63, 31, v53
	v_mov_b32_e32 v62, v61
	v_mad_u64_u32 v[62:63], s[6:7], v63, s20, v[62:63]
	v_add_u32_e32 v53, s11, v9
	v_mov_b32_e32 v61, v62
	v_mad_u64_u32 v[62:63], s[6:7], v53, s20, 0
	v_ashrrev_i32_e32 v65, 31, v53
	v_mov_b32_e32 v64, v63
	v_mad_u64_u32 v[64:65], s[6:7], v65, s20, v[64:65]
	v_add_u32_e32 v53, s11, v10
	v_mov_b32_e32 v63, v64
	v_mad_u64_u32 v[64:65], s[6:7], v53, s20, 0
	v_ashrrev_i32_e32 v67, 31, v53
	v_mov_b32_e32 v66, v65
	v_mad_u64_u32 v[66:67], s[6:7], v67, s20, v[66:67]
	v_add_u32_e32 v53, s11, v11
	v_mov_b32_e32 v65, v66
	v_mad_u64_u32 v[66:67], s[6:7], v53, s20, 0
	v_ashrrev_i32_e32 v69, 31, v53
	v_mov_b32_e32 v68, v67
	v_mad_u64_u32 v[68:69], s[6:7], v69, s20, v[68:69]
	v_add_u32_e32 v53, s11, v12
	v_mov_b32_e32 v67, v68
	v_mad_u64_u32 v[68:69], s[6:7], v53, s20, 0
	v_ashrrev_i32_e32 v71, 31, v53
	v_mov_b32_e32 v70, v69
	v_mad_u64_u32 v[70:71], s[6:7], v71, s20, v[70:71]
	v_lshl_add_u64 v[54:55], v[54:55], 2, v[2:3]
	v_mov_b32_e32 v69, v70
	s_barrier
	v_lshl_add_u64 v[56:57], v[56:57], 2, v[2:3]
	v_lshl_add_u64 v[58:59], v[58:59], 2, v[2:3]
	v_lshl_add_u64 v[60:61], v[60:61], 2, v[2:3]
	v_lshl_add_u64 v[62:63], v[62:63], 2, v[2:3]
	v_lshl_add_u64 v[64:65], v[64:65], 2, v[2:3]
	v_lshl_add_u64 v[66:67], v[66:67], 2, v[2:3]
	v_lshl_add_u64 v[68:69], v[68:69], 2, v[2:3]
	global_load_dword v53, v[54:55], off nt
	global_load_dword v72, v[56:57], off nt
	global_load_dword v73, v[58:59], off nt
	global_load_dword v74, v[60:61], off nt
	global_load_dword v75, v[62:63], off nt
	global_load_dword v76, v[64:65], off nt
	global_load_dword v77, v[66:67], off nt
	global_load_dword v78, v[68:69], off nt
	v_add_u32_e32 v54, s11, v13
	v_ashrrev_i32_e32 v57, 31, v54
	v_mad_u64_u32 v[54:55], s[6:7], v54, s20, 0
	v_mov_b32_e32 v56, v55
	v_mad_u64_u32 v[56:57], s[6:7], v57, s20, v[56:57]
	v_mov_b32_e32 v55, v56
	v_add_u32_e32 v56, s11, v14
	v_ashrrev_i32_e32 v59, 31, v56
	v_mad_u64_u32 v[56:57], s[6:7], v56, s20, 0
	v_mov_b32_e32 v58, v57
	v_mad_u64_u32 v[58:59], s[6:7], v59, s20, v[58:59]
	v_mov_b32_e32 v57, v58
	v_add_u32_e32 v58, s11, v15
	v_ashrrev_i32_e32 v61, 31, v58
	v_mad_u64_u32 v[58:59], s[6:7], v58, s20, 0
	v_mov_b32_e32 v60, v59
	v_mad_u64_u32 v[60:61], s[6:7], v61, s20, v[60:61]
	v_mov_b32_e32 v59, v60
	v_add_u32_e32 v60, s11, v16
	v_ashrrev_i32_e32 v63, 31, v60
	v_mad_u64_u32 v[60:61], s[6:7], v60, s20, 0
	v_mov_b32_e32 v62, v61
	v_mad_u64_u32 v[62:63], s[6:7], v63, s20, v[62:63]
	v_mov_b32_e32 v61, v62
	v_add_u32_e32 v62, s11, v17
	v_ashrrev_i32_e32 v65, 31, v62
	v_mad_u64_u32 v[62:63], s[6:7], v62, s20, 0
	v_mov_b32_e32 v64, v63
	v_mad_u64_u32 v[64:65], s[6:7], v65, s20, v[64:65]
	v_mov_b32_e32 v63, v64
	v_add_u32_e32 v64, s11, v18
	v_ashrrev_i32_e32 v67, 31, v64
	v_mad_u64_u32 v[64:65], s[6:7], v64, s20, 0
	v_mov_b32_e32 v66, v65
	v_mad_u64_u32 v[66:67], s[6:7], v67, s20, v[66:67]
	v_mov_b32_e32 v65, v66
	v_add_u32_e32 v66, s11, v19
	v_ashrrev_i32_e32 v69, 31, v66
	v_mad_u64_u32 v[66:67], s[6:7], v66, s20, 0
	v_mov_b32_e32 v68, v67
	v_mad_u64_u32 v[68:69], s[6:7], v69, s20, v[68:69]
	v_mov_b32_e32 v67, v68
	v_add_u32_e32 v68, s11, v20
	v_ashrrev_i32_e32 v71, 31, v68
	v_mad_u64_u32 v[68:69], s[6:7], v68, s20, 0
	v_mov_b32_e32 v70, v69
	v_mad_u64_u32 v[70:71], s[6:7], v71, s20, v[70:71]
	v_mov_b32_e32 v69, v70
	v_lshl_add_u64 v[54:55], v[54:55], 2, v[2:3]
	v_lshl_add_u64 v[56:57], v[56:57], 2, v[2:3]
	v_lshl_add_u64 v[58:59], v[58:59], 2, v[2:3]
	v_lshl_add_u64 v[60:61], v[60:61], 2, v[2:3]
	v_lshl_add_u64 v[62:63], v[62:63], 2, v[2:3]
	v_lshl_add_u64 v[64:65], v[64:65], 2, v[2:3]
	v_lshl_add_u64 v[66:67], v[66:67], 2, v[2:3]
	v_lshl_add_u64 v[2:3], v[68:69], 2, v[2:3]
	global_load_dword v54, v[54:55], off nt
	s_nop 0
	global_load_dword v55, v[56:57], off nt
	s_nop 0
	global_load_dword v56, v[58:59], off nt
	global_load_dword v57, v[60:61], off nt
	s_nop 0
	global_load_dword v58, v[62:63], off nt
	global_load_dword v59, v[64:65], off nt
	global_load_dword v60, v[66:67], off nt
	s_nop 0
	global_load_dword v2, v[2:3], off nt
	s_lshl_b32 s6, s22, 7
	s_add_u32 s4, s4, s6
	s_waitcnt vmcnt(15)
	ds_write_b32 v37, v53
	s_waitcnt vmcnt(14)
	ds_write_b32 v38, v72
	s_waitcnt vmcnt(13)
	ds_write_b32 v39, v73
	s_waitcnt vmcnt(12)
	ds_write_b32 v40, v74
	s_waitcnt vmcnt(11)
	ds_write_b32 v41, v75
	s_waitcnt vmcnt(10)
	ds_write_b32 v42, v76
	s_waitcnt vmcnt(9)
	ds_write_b32 v43, v77
	s_waitcnt vmcnt(8)
	ds_write_b32 v44, v78
	s_waitcnt vmcnt(7)
	ds_write_b32 v45, v54
	s_waitcnt vmcnt(6)
	ds_write_b32 v46, v55
	s_waitcnt vmcnt(5)
	ds_write_b32 v47, v56
	s_waitcnt vmcnt(4)
	ds_write_b32 v48, v57
	s_waitcnt vmcnt(3)
	ds_write_b32 v49, v58
	s_waitcnt vmcnt(2)
	ds_write_b32 v50, v59
	s_waitcnt vmcnt(1)
	ds_write_b32 v51, v60
	s_waitcnt vmcnt(0)
	ds_write_b32 v52, v2
	s_addc_u32 s5, s5, 0
	v_add_u32_e32 v53, s10, v21
	v_lshl_add_u64 v[2:3], s[4:5], 0, v[130:131]
	v_cmp_gt_i32_e32 vcc, s20, v53
	s_waitcnt lgkmcnt(0)
	s_barrier
	s_and_saveexec_b64 s[4:5], vcc
	s_cbranch_execz .LBB0_533
	ds_read2_b32 v[54:55], v22 offset1:65
	v_ashrrev_i32_e32 v56, 31, v53
	v_mul_lo_u32 v57, s1, v53
	v_mul_lo_u32 v56, s0, v56
	s_waitcnt lgkmcnt(0)
	v_cvt_pk_bf16_f32 v58, v54, v55
	v_mad_u64_u32 v[54:55], s[6:7], s0, v53, 0
	v_add3_u32 v55, v55, v56, v57
	v_lshl_add_u64 v[54:55], v[54:55], 1, v[2:3]
	global_store_dword v[54:55], v58, off
